# P0 weight conversion: the 8 waves of a workgroup take a 2 (k-blocks) x 4 (n-blocks) patch of tiles instead of 8 consecutive n-blocks
# baseline (speedup 1.0000x reference)
; #define INF(k) ((const float*)LDP(k))
; __global__ void __launch_bounds__(512, 2) fwd_megakernel(Args a) {
;     ...
;             { const int kb = r / 352, nb = r % 352, n0 = 32 * nb; const int up = n0 >= DFF, j = up ? n0 - DFF : n0; const int dr = (j >> 7) * 256 + 128 * up + (j & 127);
;                 transpose_item(INF(I_WGU), NGU, WGU, 2048, dr, 64 * kb, 64 * kb, n0, scr, lane); }
.LBB0_6:
	s_cmpk_gt_i32 s14, 0x25ff
	s_mov_b64 s[4:5], -1
	s_cbranch_scc0 .LBB0_10
	s_add_i32 s0, s14, 0xda00
	s_and_b32 s4, s0, 0xffff
	v_mov_b32_e32 v18, s9
	s_and_b32 s5, s4, 7
	s_lshr_b32 s4, s4, 3
	ds_read_b64 v[18:19], v18
	s_mul_i32 s6, s4, 0x2e9
	s_lshr_b32 s6, s6, 16
	s_mul_i32 s7, s6, 0x58
	s_sub_i32 s4, s4, s7
	s_lshl_b32 s4, s4, 2
	s_and_b32 s7, s5, 3
	s_or_b32 s4, s4, s7
	s_lshl_b32 s6, s6, 1
	s_lshr_b32 s5, s5, 2
	s_or_b32 s6, s6, s5
	s_lshl_b32 s0, s6, 6
	s_lshl_b32 s6, s4, 7
	s_lshl_b32 s5, s4, 5
	s_waitcnt lgkmcnt(0)
	v_readfirstlane_b32 s15, v18
	s_and_b32 s6, s6, 0x3ff80
	v_readfirstlane_b32 s7, v19
	s_add_u32 s6, s15, s6
	s_addc_u32 s7, s7, 0
	v_lshl_add_u64 v[18:19], s[6:7], 0, v[10:11]
	s_mov_b32 s6, s0
	s_mov_b32 s7, 1
	s_mov_b32 s15, 0
	s_mov_b32 s16, 32

; #define INF(k) ((const float*)LDP(k))
; __global__ void __launch_bounds__(512, 2) fwd_megakernel(Args a) {
;     ...
;             if (r < IT_IN) { const int kb = r / 304, nb = r % 304, n0 = 32 * nb; int dr = n0;
;                 if (n0 < 1280) { const int pn = n0 >> 8, c = n0 & 255, head = c >> 6, hf = (c & 63) >> 5; dr = pn * 256 + 128 * hf + head * 32; }
;                 else if (n0 >= 5632) { const int isb = n0 >= 7680, jj = isb ? n0 - 7680 : n0 - 5632; dr = 5632 + (jj >> 7) * 256 + 128 * isb + (jj & 127); }
;                 transpose_item(INF(I_WIN), INW, WIN, 2048, dr, 64 * kb, 64 * kb, n0, scr, lane); continue; } r -= IT_IN;
.LBB0_10:
	s_and_b64 vcc, exec, s[4:5]
	s_cbranch_vccz .LBB0_5
	s_and_b32 s0, s14, 7
	s_lshr_b32 s4, s14, 3
	s_mul_i32 s7, s4, 0x35f
	s_lshr_b32 s7, s7, 16
	s_mul_i32 s15, s7, 0x4c
	s_sub_i32 s15, s4, s15
	s_lshl_b32 s15, s15, 2
	s_and_b32 s4, s0, 3
	s_or_b32 s15, s15, s4
	s_lshl_b32 s7, s7, 1
	s_lshr_b32 s0, s0, 2
	s_or_b32 s7, s7, s0
	s_lshl_b32 s6, s15, 5
	s_cmp_gt_i32 s15, 39
	s_mov_b64 s[4:5], -1
	s_cbranch_scc0 .LBB0_15
	s_cmpk_lt_u32 s15, 0xb0
	s_mov_b32 s0, s6
	s_cbranch_scc1 .LBB0_14
	s_cmpk_gt_u32 s15, 0xef
	s_cselect_b32 s0, s11, 0xffffea00
	s_cselect_b32 s4, 0x80, 0
	s_add_i32 s0, s0, s6
	s_lshl_b32 s0, s0, 1
	s_and_b32 s0, s0, 0xffffff00
	s_or_b32 s0, s0, s4
	s_and_b32 s4, s6, 0x60
	s_or_b32 s0, s0, s4
	s_addk_i32 s0, 0x1600
